# static s_setprio 1 for waves 0-3 during the three GEMM phases
# speedup vs baseline: 1.0037x; 1.0037x over previous
.LBB0_229:
	v_readfirstlane_b32 s100, v180
	s_nop 3
	s_cmp_lt_u32 s100, 0x100
	s_cbranch_scc0 .Lprio_a
	s_setprio 1

.LBB0_542:
	s_and_b32 s27, s22, 3
	s_mov_b64 s[22:23], 0x80
	s_add_i32 m0, s61, 0x18000
	v_lshl_add_u64 v[6:7], v[6:7], 0, s[22:23]
	s_lshl_b32 s34, s3, 6
	s_lshl_b32 s3, s3, 13
	s_lshl_b32 s36, s27, 12
	s_waitcnt vmcnt(4)
	s_barrier
	global_load_lds_dwordx4 v[6:7], off
	v_lshl_add_u64 v[4:5], v[4:5], 0, s[22:23]
	s_add_i32 m0, s61, 0x1a000
	s_add_i32 s71, s61, 0x8000
	s_add_i32 s74, s61, 0xa000
	global_load_lds_dwordx4 v[4:5], off
	v_lshl_add_u64 v[2:3], v[2:3], 0, s[22:23]
	s_mov_b32 m0, s71
	s_add_u32 s38, s28, 0x80080
	global_load_lds_dwordx4 v[2:3], off
	v_lshl_add_u64 v[0:1], v[0:1], 0, s[22:23]
	s_mov_b32 m0, s74
	s_addc_u32 s39, s29, 0
	global_load_lds_dwordx4 v[0:1], off
	s_add_i32 m0, s61, 0x1c000
	v_lshl_add_u64 v[0:1], s[38:39], 0, v[184:185]
	global_load_lds_dwordx4 v[0:1], off
	v_lshl_add_u64 v[0:1], s[38:39], 0, v[188:189]
	s_add_i32 m0, s61, 0x1e000
	v_lshlrev_b32_e32 v2, 2, v210
	global_load_lds_dwordx4 v[0:1], off
	v_lshl_or_b32 v1, v210, 6, v141
	v_and_b32_e32 v2, 32, v2
	v_bitop3_b32 v2, v1, s3, v2 bitop3:0xde
	s_lshl_b32 s3, s27, 4
	v_or_b32_e32 v225, s34, v210
	s_or_b32 s34, s3, s34
	s_lshl_b64 s[38:39], s[34:35], 10
	s_add_u32 s3, s58, s24
	s_addc_u32 s25, s59, s25
	v_lshlrev_b32_e32 v0, 3, v140
	s_add_u32 s24, s3, s38
	v_or_b32_e32 v1, v141, v218
	v_lshl_or_b32 v227, s27, 5, v0
	s_addc_u32 s25, s25, s39
	v_lshlrev_b32_e32 v0, 4, v210
	s_ashr_i32 s76, s2, 31
	v_bitop3_b32 v226, s36, v1, v219 bitop3:0xf6
	v_lshl_or_b32 v0, v140, 8, v0
	v_mov_b32_e32 v1, v185
	s_cmp_eq_u64 s[20:21], 0
	v_lshl_add_u64 v[190:191], s[24:25], 0, v[0:1]
	s_cselect_b64 s[24:25], -1, 0
	s_lshr_b32 s3, s76, 29
	s_add_i32 s3, s2, s3
	s_ashr_i32 s27, s3, 3
	s_add_i32 s26, s27, s26
	s_ashr_i32 s27, s26, 31
	s_lshr_b32 s27, s27, 29
	s_add_i32 s27, s26, s27
	s_and_b32 s3, s3, 0xfffff8
	v_lshlrev_b32_e32 v0, 9, v180
	s_ashr_i32 s34, s27, 3
	s_and_b32 s27, s27, -8
	s_sub_i32 s3, s2, s3
	v_and_b32_e32 v0, 0xffff0000, v0
	v_lshlrev_b32_e32 v1, 12, v216
	s_sub_i32 s26, s26, s27
	s_lshl_b32 s77, s3, 8
	v_or3_b32 v0, v214, v0, v1
	s_cmp_lt_i32 s26, 0
	v_add_u32_e32 v192, v0, v215
	v_lshlrev_b32_e32 v0, 5, v217
	s_waitcnt vmcnt(6)
	s_cselect_b32 s3, 37, 36
	v_and_b32_e32 v0, 0xffff0000, v0
	s_mul_i32 s78, s26, s3
	v_or3_b32 v0, v214, v0, v1
	s_add_i32 s79, 0, 0x10000
	s_add_i32 s80, 0, 0x14000
	s_mov_b32 s75, s30
	s_add_i32 s78, s78, s34
	v_mov_b32_e32 v193, v185
	v_add_u32_e32 v194, v0, v215
	v_mov_b32_e32 v195, v185
	v_add_u32_e32 v228, s79, v226
	v_add_u32_e32 v229, 0, v2
	v_add_u32_e32 v230, s80, v226
	s_mov_b64 s[26:27], 0x3c00
	s_mov_b32 s36, 0xbfb8aa3b
	s_movk_i32 s81, 0x1000
	v_mov_b64_e32 v[196:197], 0x120
	s_barrier
	v_readfirstlane_b32 s100, v180
	s_nop 3
	s_cmp_lt_u32 s100, 0x100
	s_cbranch_scc0 .Lprio_b
	s_setprio 1

.LBB0_637:
	s_mov_b64 s[16:17], 0x80
	s_and_b32 s5, s11, 3
	s_add_i32 m0, s44, 0x18000
	v_lshl_add_u64 v[6:7], v[6:7], 0, s[16:17]
	s_lshl_b32 s40, s10, 6
	s_lshl_b32 s18, s10, 13
	s_lshl_b32 s19, s5, 12
	s_lshl_b32 s65, s5, 5
	s_lshl_b32 s66, s6, 9
	s_waitcnt vmcnt(4)
	s_barrier
	global_load_lds_dwordx4 v[6:7], off
	v_lshl_add_u64 v[4:5], v[4:5], 0, s[16:17]
	s_add_i32 m0, s44, 0x1a000
	s_add_i32 s67, s44, 0x8000
	s_add_i32 s68, s44, 0xa000
	global_load_lds_dwordx4 v[4:5], off
	v_lshl_add_u64 v[2:3], v[2:3], 0, s[16:17]
	s_mov_b32 m0, s67
	s_add_u32 s10, s8, 0x100080
	global_load_lds_dwordx4 v[2:3], off
	v_lshl_add_u64 v[0:1], v[0:1], 0, s[16:17]
	s_mov_b32 m0, s68
	s_addc_u32 s11, s9, 0
	global_load_lds_dwordx4 v[0:1], off
	s_add_i32 m0, s44, 0x1c000
	v_lshl_add_u64 v[0:1], s[10:11], 0, v[134:135]
	global_load_lds_dwordx4 v[0:1], off
	v_lshl_add_u64 v[0:1], s[10:11], 0, v[136:137]
	s_add_i32 m0, s44, 0x1e000
	v_lshrrev_b32_e32 v148, 7, v180
	global_load_lds_dwordx4 v[0:1], off
	v_lshlrev_b32_e32 v1, 2, v210
	v_lshl_or_b32 v0, v210, 6, v224
	v_and_b32_e32 v1, 32, v1
	v_bitop3_b32 v0, v0, s18, v1 bitop3:0xde
	v_or_b32_e32 v1, v218, v224
	v_bitop3_b32 v139, s19, v1, v219 bitop3:0xf6
	v_lshlrev_b32_e32 v1, 17, v148
	v_lshlrev_b32_e32 v2, 13, v216
	v_or3_b32 v1, v214, v1, v2
	v_add_u32_e32 v56, v1, v215
	v_lshlrev_b32_e32 v1, 6, v217
	v_and_b32_e32 v1, 0xfffe0000, v1
	s_mov_b64 s[10:11], 0x100080
	v_or3_b32 v1, v214, v1, v2
	v_lshl_add_u64 v[142:143], v[56:57], 0, s[10:11]
	v_add_u32_e32 v56, v1, v215
	v_or_b32_e32 v132, s40, v210
	s_waitcnt vmcnt(6)
	v_mov_b32_e32 v133, v57
	v_lshl_add_u64 v[144:145], v[56:57], 0, s[10:11]
	v_mov_b32_e32 v56, v57
	v_mov_b32_e32 v58, v57
	v_mov_b32_e32 v59, v57
	s_add_i32 s71, 0, 0x10000
	s_add_i32 s72, 0, 0x14000
	s_lshl_b32 s69, s6, 2
	v_lshlrev_b64 v[140:141], 9, v[132:133]
	v_add_u32_e32 v133, 0, v0
	s_add_i32 s75, s71, s41
	s_add_i32 s77, s72, s41
	v_mov_b64_e32 v[0:1], v[56:57]
	v_mov_b64_e32 v[4:5], v[56:57]
	v_mov_b64_e32 v[16:17], v[56:57]
	v_mov_b64_e32 v[20:21], v[56:57]
	v_mov_b64_e32 v[32:33], v[56:57]
	v_mov_b64_e32 v[36:37], v[56:57]
	v_mov_b64_e32 v[48:49], v[56:57]
	v_mov_b64_e32 v[52:53], v[56:57]
	v_mov_b64_e32 v[8:9], v[56:57]
	v_mov_b64_e32 v[12:13], v[56:57]
	v_mov_b64_e32 v[24:25], v[56:57]
	v_mov_b64_e32 v[28:29], v[56:57]
	v_mov_b64_e32 v[40:41], v[56:57]
	v_mov_b64_e32 v[44:45], v[56:57]
	v_mov_b64_e32 v[62:63], v[58:59]
	v_mov_b64_e32 v[66:67], v[58:59]
	v_mov_b64_e32 v[70:71], v[58:59]
	v_mov_b64_e32 v[74:75], v[58:59]
	v_mov_b64_e32 v[86:87], v[58:59]
	v_mov_b64_e32 v[90:91], v[58:59]
	v_mov_b64_e32 v[102:103], v[58:59]
	v_mov_b64_e32 v[106:107], v[58:59]
	v_mov_b64_e32 v[118:119], v[58:59]
	v_mov_b64_e32 v[122:123], v[58:59]
	v_mov_b64_e32 v[78:79], v[58:59]
	v_mov_b64_e32 v[82:83], v[58:59]
	v_mov_b64_e32 v[94:95], v[58:59]
	v_mov_b64_e32 v[98:99], v[58:59]
	v_mov_b64_e32 v[110:111], v[58:59]
	v_mov_b64_e32 v[114:115], v[58:59]
	v_mov_b64_e32 v[126:127], v[58:59]
	v_mov_b64_e32 v[130:131], v[58:59]
	s_add_i32 s69, s69, s3
	s_or_b32 s70, s33, 0xffffff00
	v_and_b32_e32 v138, 12, v177
	s_lshl_b32 s18, s65, 1
	s_add_i32 s73, s44, 0xc000
	s_add_i32 s74, s44, 0xe000
	s_add_i32 s76, s75, 0x2000
	s_add_i32 s78, s77, 0x2000
	s_add_i32 s79, 0, 0x18000
	v_mov_b64_e32 v[2:3], v[58:59]
	v_mov_b64_e32 v[6:7], v[58:59]
	v_mov_b64_e32 v[18:19], v[58:59]
	v_mov_b64_e32 v[22:23], v[58:59]
	v_mov_b64_e32 v[34:35], v[58:59]
	v_mov_b64_e32 v[38:39], v[58:59]
	v_mov_b64_e32 v[50:51], v[58:59]
	v_mov_b64_e32 v[54:55], v[58:59]
	v_mov_b64_e32 v[10:11], v[58:59]
	v_mov_b64_e32 v[14:15], v[58:59]
	v_mov_b64_e32 v[26:27], v[58:59]
	v_mov_b64_e32 v[30:31], v[58:59]
	v_mov_b64_e32 v[42:43], v[58:59]
	v_mov_b64_e32 v[46:47], v[58:59]
	v_mov_b64_e32 v[60:61], v[56:57]
	v_mov_b64_e32 v[64:65], v[56:57]
	v_mov_b64_e32 v[68:69], v[56:57]
	v_mov_b64_e32 v[72:73], v[56:57]
	v_mov_b64_e32 v[84:85], v[56:57]
	v_mov_b64_e32 v[88:89], v[56:57]
	v_mov_b64_e32 v[100:101], v[56:57]
	v_mov_b64_e32 v[104:105], v[56:57]
	v_mov_b64_e32 v[116:117], v[56:57]
	v_mov_b64_e32 v[120:121], v[56:57]
	v_mov_b64_e32 v[76:77], v[56:57]
	v_mov_b64_e32 v[80:81], v[56:57]
	v_mov_b64_e32 v[92:93], v[56:57]
	v_mov_b64_e32 v[96:97], v[56:57]
	v_mov_b64_e32 v[108:109], v[56:57]
	v_mov_b64_e32 v[112:113], v[56:57]
	v_mov_b64_e32 v[124:125], v[56:57]
	v_mov_b64_e32 v[128:129], v[56:57]
	s_mov_b32 s19, s4
	s_mov_b32 s6, s66
	s_mov_b32 s80, 0
	s_barrier
	v_readfirstlane_b32 s100, v180
	s_nop 3
	s_cmp_lt_u32 s100, 0x100
	s_cbranch_scc0 .Lprio_c
	s_setprio 1
